# stack4 + SGU: group-invariant spatial-weight/bias/gain vectors kept in unused VGPRs (reloaded only when the group changes), k-step fragment reads issued ahead of their MFMAs with counted waits, row su
# speedup vs baseline: 1.0007x; 1.0007x over previous
.LBB0_496:
	s_movk_i32 s4, 0xa0
	s_mov_b32 s3, 40
	s_mov_b32 s2, 48
	s_mov_b32 s0, 32
	s_cmpk_gt_i32 s11, 0x3ff
	s_cbranch_scc1 .LBB0_524
	s_load_dwordx2 s[4:5], s[58:59], s4 offset:0x0
	v_writelane_b32 v255, s92, 24
	s_load_dwordx2 s[8:9], s[58:59], s3 offset:0x0
	s_load_dwordx2 s[12:13], s[58:59], s2 offset:0x0
	s_load_dwordx2 s[14:15], s[58:59], s0 offset:0x0
	v_writelane_b32 v255, s93, 25
	s_mov_b32 s61, s89
	s_waitcnt lgkmcnt(0)
	s_add_u32 s0, s4, 0xe100000
	s_mov_b32 s2, s60
	v_mbcnt_lo_u32_b32 v0, -1, s1
	s_addc_u32 s1, s5, 0
	s_lshl_b64 s[16:17], s[60:61], 18
	v_writelane_b32 v255, s2, 20
	s_lshl_b64 s[18:19], s[60:61], 11
	v_mbcnt_hi_u32_b32 v20, -1, v0
	v_writelane_b32 v255, s3, 21
	s_add_u32 s2, s4, 0xa100000
	s_addc_u32 s3, s5, 0
	s_add_u32 s90, s8, s16
	s_addc_u32 s91, s9, s17
	s_add_u32 s92, s12, s18
	s_addc_u32 s93, s13, s19
	s_add_u32 s12, s14, s18
	s_addc_u32 s13, s15, s19
	s_add_u32 s14, s4, 0x10100000
	v_and_b32_e32 v21, 15, v20
	v_readlane_b32 s7, v255, 3
	s_addc_u32 s15, s5, 0
	s_lshl_b32 s4, s11, 8
	v_or_b32_e32 v102, s7, v21
	s_lshl_b32 s7, s11, 7
	s_and_b32 s4, s4, 0x300
	v_add_u32_e32 v0, s51, v20
	s_add_u32 s4, s14, s4
	v_ashrrev_i32_e32 v112, 4, v0
	s_addc_u32 s5, s15, 0
	v_lshlrev_b32_e32 v0, 4, v21
	s_lshl_b32 s8, s11, 5
	v_lshl_add_u64 v[2:3], s[4:5], 0, v[0:1]
	s_and_b32 s4, s8, 0xffffff80
	v_add_u32_e32 v4, s4, v112
	v_ashrrev_i32_e32 v5, 31, v4
	v_lshlrev_b64 v[4:5], 10, v[4:5]
	v_lshl_add_u64 v[6:7], v[2:3], 0, v[4:5]
	s_mov_b32 s4, 0x18000
	v_add_co_u32_e32 v2, vcc, s4, v6
	s_mov_b32 s4, 0x10000
	s_nop 0
	v_addc_co_u32_e32 v3, vcc, 0, v7, vcc
	v_add_co_u32_e32 v8, vcc, s97, v6
	global_load_dwordx4 v[2:5], v[2:3], off
	s_nop 0
	global_load_dwordx4 v[14:17], v[6:7], off
	v_addc_co_u32_e32 v9, vcc, 0, v7, vcc
	v_add_co_u32_e32 v6, vcc, s4, v6
	v_ashrrev_i32_e32 v22, 1, v20
	s_nop 0
	v_addc_co_u32_e32 v7, vcc, 0, v7, vcc
	global_load_dwordx4 v[10:13], v[8:9], off
	s_nop 0
	global_load_dwordx4 v[6:9], v[6:7], off
	v_and_b32_e32 v104, -8, v22
	v_lshlrev_b32_e32 v18, 5, v21
	v_mov_b32_e32 v19, v1
	v_lshl_add_u64 v[106:107], s[12:13], 0, v[18:19]
	v_lshl_add_u64 v[108:109], s[14:15], 0, v[0:1]
	v_bfe_u32 v0, v20, 2, 2
	v_cmp_gt_i32_e64 s[12:13], v104, v102
	v_lshlrev_b32_e32 v19, 3, v20
	v_or_b32_e32 v0, v104, v0
	s_movk_i32 s9, 0x110
	v_writelane_b32 v255, s12, 26
	v_lshlrev_b32_e32 v18, 2, v20
	v_and_b32_e32 v19, 24, v19
	v_mul_lo_u32 v0, v0, s9
	v_writelane_b32 v255, s13, 27
	v_cmp_gt_i32_e64 s[12:13], v102, v104
	v_xor_b32_e32 v113, 4, v18
	v_xor_b32_e32 v114, 8, v18
	v_xor_b32_e32 v115, 16, v18
	v_xor_b32_e32 v116, 32, v18
	v_lshlrev_b32_e32 v18, 4, v20
	v_add3_u32 v117, 0, v0, v19
	v_writelane_b32 v255, s12, 28
	v_or_b32_e32 v0, 3, v104
	v_and_b32_e32 v18, 0xc0, v18
	v_writelane_b32 v255, s13, 29
	v_cmp_gt_i32_e64 s[12:13], v0, v102
	v_add3_u32 v18, 0, v18, v19
	v_or_b32_e32 v19, 2, v104
	v_writelane_b32 v255, s12, 30
	v_or_b32_e32 v0, 5, v104
	v_cmp_gt_i32_e64 s[14:15], v0, v102
	v_writelane_b32 v255, s13, 31
	v_cmp_gt_i32_e64 s[12:13], v19, v102
	v_or_b32_e32 v19, 4, v104
	v_or_b32_e32 v0, 7, v22
	v_cmp_gt_i32_e64 s[16:17], v19, v102
	v_or_b32_e32 v19, 6, v104
	v_cmp_gt_i32_e64 s[18:19], v0, v102
	v_add_u32_e32 v0, 32, v104
	v_cmp_gt_i32_e64 s[20:21], v19, v102
	v_or_b32_e32 v19, 3, v0
	v_or_b32_e32 v20, 2, v0
	v_cmp_gt_i32_e64 s[26:27], v19, v102
	v_or_b32_e32 v19, 5, v0
	v_cmp_gt_i32_e64 s[22:23], v0, v102
	v_cmp_gt_i32_e64 s[24:25], v102, v0
	v_cmp_gt_i32_e64 s[28:29], v20, v102
	v_or_b32_e32 v20, 4, v0
	v_cmp_gt_i32_e64 s[30:31], v19, v102
	v_or_b32_e32 v19, 7, v0
	v_or_b32_e32 v0, 6, v0
	v_cmp_gt_i32_e64 s[38:39], v0, v102
	v_add_u32_e32 v0, 64, v104
	v_cmp_gt_i32_e64 s[36:37], v19, v102
	v_or_b32_e32 v19, 3, v0
	v_cmp_gt_i32_e64 s[34:35], v20, v102
	v_or_b32_e32 v20, 2, v0
	v_cmp_gt_i32_e64 s[44:45], v19, v102
	v_or_b32_e32 v19, 5, v0
	v_cmp_gt_i32_e64 s[40:41], v0, v102
	v_cmp_gt_i32_e64 s[42:43], v102, v0
	v_cmp_gt_i32_e64 s[46:47], v20, v102
	v_or_b32_e32 v20, 4, v0
	v_cmp_gt_i32_e64 s[48:49], v19, v102
	v_or_b32_e32 v19, 7, v0
	v_or_b32_e32 v0, 6, v0
	v_cmp_gt_i32_e64 s[54:55], v0, v102
	v_add_u32_e32 v0, 0x60, v104
	v_cmp_gt_i32_e64 s[52:53], v19, v102
	v_or_b32_e32 v19, 3, v0
	v_cmp_gt_i32_e64 s[50:51], v20, v102
	v_or_b32_e32 v20, 2, v0
	v_cmp_gt_i32_e64 s[60:61], v19, v102
	v_or_b32_e32 v19, 5, v0
	v_cmp_gt_i32_e64 s[56:57], v0, v102
	v_cmp_gt_i32_e64 s[58:59], v102, v0
	v_cmp_gt_i32_e64 s[62:63], v20, v102
	v_or_b32_e32 v20, 4, v0
	v_cmp_gt_i32_e64 s[64:65], v19, v102
	v_or_b32_e32 v19, 7, v0
	v_or_b32_e32 v0, 6, v0
	v_writelane_b32 v255, s12, 32
	v_cmp_gt_i32_e64 s[70:71], v0, v102
	v_mul_lo_u32 v0, v112, s9
	v_ashrrev_i32_e32 v103, 31, v102
	v_ashrrev_i32_e32 v105, 31, v104
	v_cmp_eq_u32_e64 s[4:5], 0, v21
	v_lshl_add_u32 v118, v104, 2, 0
	v_writelane_b32 v255, s13, 33
	v_cmp_gt_i32_e64 s[66:67], v20, v102
	v_cmp_gt_i32_e64 s[68:69], v19, v102
	v_lshl_add_u32 v119, v112, 2, 0
	s_lshl_b32 s9, s6, 5
	s_lshl_b32 s10, s6, 7
	v_add_u32_e32 v120, v18, v0
	s_mov_b32 s100, -1
	s_branch .LBB0_499

.LBB0_499:
	s_and_b32 s88, s7, 0x180
	s_cmp_eq_u32 s88, s100
	s_cbranch_scc1 .Lsgu_have_w
	v_add_u32_e32 v172, s88, v102
	v_ashrrev_i32_e32 v173, 31, v172
	v_lshl_add_u64 v[172:173], v[172:173], 2, s[92:93]
	global_load_dword v162, v[172:173], off
	v_lshl_add_u64 v[172:173], s[88:89], 0, v[102:103]
	v_lshlrev_b64 v[172:173], 9, v[172:173]
	v_lshl_add_u64 v[172:173], s[90:91], 0, v[172:173]
	v_lshl_add_u64 v[172:173], v[104:105], 2, v[172:173]
	global_load_dwordx4 v[130:133], v[172:173], off offset:16
	global_load_dwordx4 v[134:137], v[172:173], off
	global_load_dwordx4 v[138:141], v[172:173], off offset:144
	global_load_dwordx4 v[142:145], v[172:173], off offset:128
	global_load_dwordx4 v[146:149], v[172:173], off offset:272
	global_load_dwordx4 v[150:153], v[172:173], off offset:256
	global_load_dwordx4 v[154:157], v[172:173], off offset:400
	global_load_dwordx4 v[158:161], v[172:173], off offset:384
	s_lshl_b32 s101, s88, 2
	v_mov_b32_e32 v175, 0
	v_mov_b32_e32 v174, s101
	v_lshl_add_u64 v[172:173], v[106:107], 0, v[174:175]
	global_load_dwordx4 v[164:167], v[172:173], off offset:16
	global_load_dwordx4 v[168:171], v[172:173], off
	s_waitcnt vmcnt(0)
	s_mov_b32 s100, s88
.Lsgu_have_w:
	v_add_u32_e32 v18, s88, v102
	v_ashrrev_i32_e32 v19, 31, v18
	v_lshl_add_u64 v[18:19], v[18:19], 2, s[92:93]
	v_mov_b32_e32 v0, v162
	v_lshl_add_u64 v[18:19], s[88:89], 0, v[102:103]
	v_readlane_b32 s12, v255, 5
	v_lshlrev_b64 v[18:19], 9, v[18:19]
	v_readlane_b32 s13, v255, 6
	v_lshl_add_u64 v[18:19], s[90:91], 0, v[18:19]
	v_mov_b32_e32 v66, 0
	v_cndmask_b32_e64 v20, 0, 1, s[12:13]
	v_cmp_ne_u32_e64 s[78:79], 1, v20
	s_andn2_b64 vcc, exec, s[12:13]
	v_lshl_add_u64 v[18:19], v[104:105], 2, v[18:19]
	v_mov_b32_e32 v90, 0
	v_mov_b32_e32 v91, 0
	v_mov_b32_e32 v92, 0
	v_mov_b32_e32 v93, 0
	v_mov_b32_e32 v94, 0
	v_mov_b32_e32 v95, 0
	v_mov_b32_e32 v96, 0
	v_mov_b32_e32 v97, 0
	s_cbranch_vccnz .LBB0_501
	v_mov_b64_e32 v[90:91], v[130:131]
	v_mov_b64_e32 v[92:93], v[132:133]
	v_mov_b64_e32 v[94:95], v[134:135]
	v_mov_b64_e32 v[96:97], v[136:137]
.LBB0_501:
	v_readlane_b32 s12, v255, 7
	v_readlane_b32 s13, v255, 8
	s_andn2_b64 vcc, exec, s[12:13]
	v_mov_b32_e32 v67, 0
	v_cndmask_b32_e64 v20, 0, 1, s[12:13]
	v_cmp_ne_u32_e64 s[76:77], 1, v20
	v_mov_b32_e32 v68, 0
	v_mov_b32_e32 v69, 0
	v_mov_b32_e32 v82, 0
	v_mov_b32_e32 v83, 0
	v_mov_b32_e32 v84, 0
	v_mov_b32_e32 v85, 0
	s_cbranch_vccnz .LBB0_503
	v_mov_b64_e32 v[66:67], v[138:139]
	v_mov_b64_e32 v[68:69], v[140:141]
	v_mov_b64_e32 v[82:83], v[142:143]
	v_mov_b64_e32 v[84:85], v[144:145]
.LBB0_503:
	v_readlane_b32 s12, v255, 9
	v_readlane_b32 s13, v255, 10
	v_mov_b32_e32 v34, 0
	s_andn2_b64 vcc, exec, s[12:13]
	v_cndmask_b32_e64 v20, 0, 1, s[12:13]
	v_cmp_ne_u32_e64 s[74:75], 1, v20
	v_mov_b32_e32 v42, 0
	v_mov_b32_e32 v43, 0
	v_mov_b32_e32 v44, 0
	v_mov_b32_e32 v45, 0
	v_mov_b32_e32 v46, 0
	v_mov_b32_e32 v47, 0
	v_mov_b32_e32 v48, 0
	v_mov_b32_e32 v49, 0
	s_cbranch_vccnz .LBB0_505
	v_mov_b64_e32 v[42:43], v[146:147]
	v_mov_b64_e32 v[44:45], v[148:149]
	v_mov_b64_e32 v[46:47], v[150:151]
	v_mov_b64_e32 v[48:49], v[152:153]
.LBB0_505:
	v_readlane_b32 s12, v255, 11
	v_readlane_b32 s13, v255, 12
	s_andn2_b64 vcc, exec, s[12:13]
	v_mov_b32_e32 v35, 0
	v_cndmask_b32_e64 v20, 0, 1, s[12:13]
	v_cmp_ne_u32_e64 s[72:73], 1, v20
	v_mov_b32_e32 v36, 0
	v_mov_b32_e32 v37, 0
	v_mov_b32_e32 v38, 0
	v_mov_b32_e32 v39, 0
	v_mov_b32_e32 v40, 0
	v_mov_b32_e32 v41, 0
	s_cbranch_vccnz .LBB0_507
	v_mov_b64_e32 v[34:35], v[154:155]
	v_mov_b64_e32 v[36:37], v[156:157]
	v_mov_b64_e32 v[38:39], v[158:159]
	v_mov_b64_e32 v[40:41], v[160:161]
.LBB0_507:
	s_and_b32 s12, s8, 0xffffff80
	v_add_u32_e32 v110, s12, v102
	s_lshl_b32 s94, s88, 1
	s_lshl_b32 s88, s88, 2
	v_ashrrev_i32_e32 v111, 31, v110
	v_lshl_add_u64 v[18:19], v[106:107], 0, s[88:89]
	v_mov_b64_e32 v[50:51], v[164:165]
	v_mov_b64_e32 v[52:53], v[166:167]
	v_mov_b64_e32 v[54:55], v[168:169]
	v_mov_b64_e32 v[56:57], v[170:171]
	v_lshlrev_b64 v[18:19], 10, v[110:111]
	v_lshl_add_u64 v[18:19], s[0:1], 0, v[18:19]
	s_mov_b32 s95, s89
	v_lshl_add_u64 v[18:19], v[18:19], 0, s[94:95]
	v_lshl_add_u64 v[18:19], v[104:105], 1, v[18:19]
	global_load_dwordx4 v[30:33], v[18:19], off
	global_load_dwordx4 v[26:29], v[18:19], off offset:64
	global_load_dwordx4 v[22:25], v[18:19], off offset:128
	s_nop 0
	global_load_dwordx4 v[18:21], v[18:19], off offset:192
	s_waitcnt vmcnt(4)
	v_lshlrev_b32_e32 v58, 16, v14
	v_and_b32_e32 v59, 0xffff0000, v14
	v_lshlrev_b32_e32 v60, 16, v15
	v_and_b32_e32 v61, 0xffff0000, v15
	v_lshlrev_b32_e32 v62, 16, v16
	v_and_b32_e32 v63, 0xffff0000, v16
	v_lshlrev_b32_e32 v16, 16, v17
	v_and_b32_e32 v17, 0xffff0000, v17
	v_pk_mul_f32 v[14:15], v[58:59], v[58:59]
	v_pk_mul_f32 v[64:65], v[60:61], v[60:61]
	v_pk_mul_f32 v[70:71], v[62:63], v[62:63]
	v_pk_mul_f32 v[72:73], v[16:17], v[16:17]
	v_add_f32_e32 v70, v70, v71
	v_add_f32_e32 v72, v72, v73
	v_add_f32_e32 v64, v64, v65
	v_add_f32_e32 v14, v14, v15
	v_add_f32_e32 v15, v70, v72
	v_add_f32_e32 v14, v14, v64
	v_add_f32_e32 v14, v14, v15
	s_waitcnt lgkmcnt(0)
	s_nop 1
	v_add_f32_dpp v14, v14, v14 quad_perm:[1,0,3,2] row_mask:0xf bank_mask:0xf
	s_waitcnt lgkmcnt(0)
	s_nop 1
	v_add_f32_dpp v14, v14, v14 quad_perm:[2,3,0,1] row_mask:0xf bank_mask:0xf
	s_waitcnt lgkmcnt(0)
	s_nop 1
	v_add_f32_dpp v14, v14, v14 row_half_mirror row_mask:0xf bank_mask:0xf
	s_nop 1
	v_add_f32_dpp v14, v14, v14 row_mirror row_mask:0xf bank_mask:0xf
	s_waitcnt vmcnt(4)
	v_pk_mul_f32 v[62:63], v[50:51], v[62:63]
	s_waitcnt vmcnt(4)
	v_pk_mul_f32 v[58:59], v[54:55], v[58:59]
	v_pk_mul_f32 v[60:61], v[56:57], v[60:61]
	v_pk_mul_f32 v[16:17], v[52:53], v[16:17]
	v_cvt_pk_bf16_f32 v58, v58, v59
	v_cvt_pk_bf16_f32 v59, v60, v61
	v_cvt_pk_bf16_f32 v60, v62, v63
	v_cvt_pk_bf16_f32 v61, v16, v17
	ds_write2_b64 v120, v[58:59], v[60:61] offset1:4
	s_and_saveexec_b64 s[84:85], s[4:5]
	s_cbranch_execz .LBB0_509
	s_waitcnt lgkmcnt(1)
	v_fmamk_f32 v14, v14, 0x3c000000, v251
	v_rsq_f32_e32 v14, v14
	ds_write_b32 v119, v14 offset:36864
.LBB0_509:
	s_or_b64 exec, exec, s[84:85]
	v_lshlrev_b32_e32 v14, 16, v10
	s_waitcnt lgkmcnt(1)
	v_and_b32_e32 v15, 0xffff0000, v10
	v_lshlrev_b32_e32 v10, 16, v11
	v_and_b32_e32 v11, 0xffff0000, v11
	v_pk_mul_f32 v[16:17], v[14:15], v[14:15]
	v_pk_mul_f32 v[14:15], v[54:55], v[14:15]
	v_pk_mul_f32 v[58:59], v[10:11], v[10:11]
	v_pk_mul_f32 v[10:11], v[56:57], v[10:11]
	v_cvt_pk_bf16_f32 v14, v14, v15
	v_cvt_pk_bf16_f32 v15, v10, v11
	v_lshlrev_b32_e32 v10, 16, v12
	v_and_b32_e32 v11, 0xffff0000, v12
	v_pk_mul_f32 v[60:61], v[10:11], v[10:11]
	v_pk_mul_f32 v[10:11], v[50:51], v[10:11]
	v_lshlrev_b32_e32 v62, 16, v13
	v_and_b32_e32 v63, 0xffff0000, v13
	v_cvt_pk_bf16_f32 v12, v10, v11
	v_pk_mul_f32 v[10:11], v[62:63], v[62:63]
	v_add_f32_e32 v13, v16, v17
	v_add_f32_e32 v10, v10, v11
	v_add_f32_e32 v11, v60, v61
	v_add_f32_e32 v10, v11, v10
	v_add_f32_e32 v11, v58, v59
	v_add_f32_e32 v11, v13, v11
	v_add_f32_e32 v10, v11, v10
	v_pk_mul_f32 v[16:17], v[52:53], v[62:63]
	s_waitcnt lgkmcnt(0)
	s_nop 1
	v_add_f32_dpp v10, v10, v10 quad_perm:[1,0,3,2] row_mask:0xf bank_mask:0xf
	v_cvt_pk_bf16_f32 v13, v16, v17
	v_add_u32_e32 v16, 0x2000, v120
	ds_write2_b64 v16, v[14:15], v[12:13] offset0:64 offset1:68
	s_waitcnt lgkmcnt(1)
	s_nop 1
	v_add_f32_dpp v10, v10, v10 quad_perm:[2,3,0,1] row_mask:0xf bank_mask:0xf
	s_waitcnt lgkmcnt(0)
	s_nop 1
	v_add_f32_dpp v10, v10, v10 row_half_mirror row_mask:0xf bank_mask:0xf
	s_nop 1
	v_add_f32_dpp v10, v10, v10 row_mirror row_mask:0xf bank_mask:0xf
	s_and_saveexec_b64 s[84:85], s[4:5]
	s_cbranch_execz .LBB0_511
	s_waitcnt lgkmcnt(0)
	v_fmamk_f32 v10, v10, 0x3c000000, v251
	v_rsq_f32_e32 v10, v10
	ds_write_b32 v119, v10 offset:36992
.LBB0_511:
	s_or_b64 exec, exec, s[84:85]
	v_lshlrev_b32_e32 v10, 16, v6
	s_waitcnt lgkmcnt(0)
	v_and_b32_e32 v11, 0xffff0000, v6
	v_lshlrev_b32_e32 v6, 16, v7
	v_and_b32_e32 v7, 0xffff0000, v7
	v_pk_mul_f32 v[12:13], v[10:11], v[10:11]
	v_pk_mul_f32 v[10:11], v[54:55], v[10:11]
	v_pk_mul_f32 v[14:15], v[6:7], v[6:7]
	v_pk_mul_f32 v[6:7], v[56:57], v[6:7]
	v_cvt_pk_bf16_f32 v10, v10, v11
	v_cvt_pk_bf16_f32 v11, v6, v7
	v_lshlrev_b32_e32 v6, 16, v8
	v_and_b32_e32 v7, 0xffff0000, v8
	v_pk_mul_f32 v[16:17], v[6:7], v[6:7]
	v_pk_mul_f32 v[6:7], v[50:51], v[6:7]
	v_lshlrev_b32_e32 v58, 16, v9
	v_and_b32_e32 v59, 0xffff0000, v9
	v_cvt_pk_bf16_f32 v8, v6, v7
	v_pk_mul_f32 v[6:7], v[58:59], v[58:59]
	v_add_f32_e32 v9, v12, v13
	v_add_f32_e32 v6, v6, v7
	v_add_f32_e32 v7, v16, v17
	v_add_f32_e32 v6, v7, v6
	v_add_f32_e32 v7, v14, v15
	v_add_f32_e32 v7, v9, v7
	v_add_f32_e32 v6, v7, v6
	v_pk_mul_f32 v[12:13], v[52:53], v[58:59]
	s_waitcnt lgkmcnt(0)
	s_nop 1
	v_add_f32_dpp v6, v6, v6 quad_perm:[1,0,3,2] row_mask:0xf bank_mask:0xf
	v_cvt_pk_bf16_f32 v9, v12, v13
	v_add_u32_e32 v12, 0x4000, v120
	ds_write2_b64 v12, v[10:11], v[8:9] offset0:128 offset1:132
	s_waitcnt lgkmcnt(1)
	s_nop 1
	v_add_f32_dpp v6, v6, v6 quad_perm:[2,3,0,1] row_mask:0xf bank_mask:0xf
	s_waitcnt lgkmcnt(0)
	s_nop 1
	v_add_f32_dpp v6, v6, v6 row_half_mirror row_mask:0xf bank_mask:0xf
	s_nop 1
	v_add_f32_dpp v6, v6, v6 row_mirror row_mask:0xf bank_mask:0xf
	s_and_saveexec_b64 s[84:85], s[4:5]
	s_cbranch_execz .LBB0_513
	s_waitcnt lgkmcnt(0)
	v_fmamk_f32 v6, v6, 0x3c000000, v251
	v_rsq_f32_e32 v6, v6
	ds_write_b32 v119, v6 offset:37120
.LBB0_513:
	s_or_b64 exec, exec, s[84:85]
	v_lshlrev_b32_e32 v6, 16, v2
	s_waitcnt lgkmcnt(0)
	v_and_b32_e32 v7, 0xffff0000, v2
	v_lshlrev_b32_e32 v2, 16, v3
	v_and_b32_e32 v3, 0xffff0000, v3
	v_pk_mul_f32 v[8:9], v[6:7], v[6:7]
	v_pk_mul_f32 v[6:7], v[54:55], v[6:7]
	v_pk_mul_f32 v[10:11], v[2:3], v[2:3]
	v_pk_mul_f32 v[2:3], v[56:57], v[2:3]
	v_cvt_pk_bf16_f32 v6, v6, v7
	v_cvt_pk_bf16_f32 v7, v2, v3
	v_lshlrev_b32_e32 v2, 16, v4
	v_and_b32_e32 v3, 0xffff0000, v4
	v_pk_mul_f32 v[12:13], v[2:3], v[2:3]
	v_pk_mul_f32 v[2:3], v[50:51], v[2:3]
	v_lshlrev_b32_e32 v14, 16, v5
	v_and_b32_e32 v15, 0xffff0000, v5
	v_cvt_pk_bf16_f32 v4, v2, v3
	v_pk_mul_f32 v[2:3], v[14:15], v[14:15]
	v_add_f32_e32 v5, v8, v9
	v_add_f32_e32 v2, v2, v3
	v_add_f32_e32 v3, v12, v13
	v_add_f32_e32 v2, v3, v2
	v_add_f32_e32 v3, v10, v11
	v_add_f32_e32 v3, v5, v3
	v_add_f32_e32 v2, v3, v2
	v_pk_mul_f32 v[8:9], v[52:53], v[14:15]
	s_waitcnt lgkmcnt(0)
	s_nop 1
	v_add_f32_dpp v2, v2, v2 quad_perm:[1,0,3,2] row_mask:0xf bank_mask:0xf
	v_cvt_pk_bf16_f32 v5, v8, v9
	v_add_u32_e32 v8, 0x6000, v120
	ds_write2_b64 v8, v[6:7], v[4:5] offset0:192 offset1:196
	s_waitcnt lgkmcnt(1)
	s_nop 1
	v_add_f32_dpp v2, v2, v2 quad_perm:[2,3,0,1] row_mask:0xf bank_mask:0xf
	s_waitcnt lgkmcnt(0)
	s_nop 1
	v_add_f32_dpp v2, v2, v2 row_half_mirror row_mask:0xf bank_mask:0xf
	s_nop 1
	v_add_f32_dpp v2, v2, v2 row_mirror row_mask:0xf bank_mask:0xf
	s_and_saveexec_b64 s[84:85], s[4:5]
	s_cbranch_execz .LBB0_515
	s_waitcnt lgkmcnt(0)
	v_fmamk_f32 v2, v2, 0x3c000000, v251
	v_rsq_f32_e32 v2, v2
	ds_write_b32 v119, v2 offset:37248

.LBB0_520:
	v_cndmask_b32_e64 v87, 0, v83, s[24:25]
	v_cndmask_b32_e64 v86, v82, 0, s[22:23]
	v_cndmask_b32_e64 v88, v84, 0, s[28:29]
	v_cndmask_b32_e64 v89, v85, 0, s[26:27]
	v_cndmask_b32_e64 v90, v66, 0, s[34:35]
	v_cndmask_b32_e64 v91, v67, 0, s[30:31]
	v_cndmask_b32_e64 v92, v68, 0, s[38:39]
	v_cndmask_b32_e64 v93, v69, 0, s[36:37]
	ds_read_b128 v[66:69], v118 offset:36992
	ds_read_b128 v[82:85], v118 offset:37008
	s_waitcnt lgkmcnt(1)
	v_pk_mul_f32 v[66:67], v[66:67], v[86:87]
	v_pk_mul_f32 v[68:69], v[68:69], v[88:89]
	v_cvt_pk_bf16_f32 v66, v66, v67
	v_cvt_pk_bf16_f32 v67, v68, v69
	s_waitcnt lgkmcnt(0)
	v_pk_mul_f32 v[68:69], v[82:83], v[90:91]
	v_pk_mul_f32 v[82:83], v[84:85], v[92:93]
	v_cvt_pk_bf16_f32 v68, v68, v69
	v_cvt_pk_bf16_f32 v69, v82, v83
	ds_read_b64_tr_b16 v[180:181], v117 offset:8704
	ds_read_b64_tr_b16 v[182:183], v117 offset:9792
	ds_read_b64_tr_b16 v[184:185], v117 offset:8768
	ds_read_b64_tr_b16 v[186:187], v117 offset:9856
	ds_read_b64_tr_b16 v[188:189], v117 offset:8800
	ds_read_b64_tr_b16 v[190:191], v117 offset:9888
	ds_read_b64_tr_b16 v[192:193], v117 offset:8832
	ds_read_b64_tr_b16 v[194:195], v117 offset:9920
	ds_read_b64_tr_b16 v[196:197], v117 offset:8864
	ds_read_b64_tr_b16 v[198:199], v117 offset:9952
	ds_read_b64_tr_b16 v[200:201], v117 offset:8896
	ds_read_b64_tr_b16 v[202:203], v117 offset:9984
	ds_read_b64_tr_b16 v[204:205], v117 offset:8736
	ds_read_b64_tr_b16 v[206:207], v117 offset:9824
	ds_read_b64_tr_b16 v[208:209], v117 offset:8928
	ds_read_b64_tr_b16 v[210:211], v117 offset:10016
	s_waitcnt lgkmcnt(14)
	v_mfma_f32_16x16x32_bf16 v[78:81], v[180:183], v[66:69], v[78:81]
	s_waitcnt lgkmcnt(12)
	v_mfma_f32_16x16x32_bf16 v[62:65], v[184:187], v[66:69], v[62:65]
	s_waitcnt lgkmcnt(10)
	v_mfma_f32_16x16x32_bf16 v[54:57], v[188:191], v[66:69], v[54:57]
	s_waitcnt lgkmcnt(8)
	v_mfma_f32_16x16x32_bf16 v[70:73], v[192:195], v[66:69], v[70:73]
	s_waitcnt lgkmcnt(6)
	v_mfma_f32_16x16x32_bf16 v[58:61], v[196:199], v[66:69], v[58:61]
	s_waitcnt lgkmcnt(4)
	v_mfma_f32_16x16x32_bf16 v[50:53], v[200:203], v[66:69], v[50:53]
	s_waitcnt lgkmcnt(2)
	v_mfma_f32_16x16x32_bf16 v[74:77], v[204:207], v[66:69], v[74:77]
	s_waitcnt lgkmcnt(0)
	v_mfma_f32_16x16x32_bf16 v[86:89], v[208:211], v[66:69], v[98:101]
	s_and_b64 vcc, exec, s[74:75]
	s_cbranch_vccnz .LBB0_518
.LBB0_521:
	v_cndmask_b32_e64 v67, 0, v47, s[42:43]
	v_cndmask_b32_e64 v66, v46, 0, s[40:41]
	v_cndmask_b32_e64 v68, v48, 0, s[46:47]
	v_cndmask_b32_e64 v69, v49, 0, s[44:45]
	v_cndmask_b32_e64 v82, v42, 0, s[50:51]
	v_cndmask_b32_e64 v83, v43, 0, s[48:49]
	v_cndmask_b32_e64 v84, v44, 0, s[54:55]
	v_cndmask_b32_e64 v85, v45, 0, s[52:53]
	ds_read_b128 v[42:45], v118 offset:37120
	ds_read_b128 v[46:49], v118 offset:37136
	s_waitcnt lgkmcnt(1)
	v_pk_mul_f32 v[42:43], v[42:43], v[66:67]
	v_pk_mul_f32 v[44:45], v[44:45], v[68:69]
	v_cvt_pk_bf16_f32 v42, v42, v43
	v_cvt_pk_bf16_f32 v43, v44, v45
	s_waitcnt lgkmcnt(0)
	v_pk_mul_f32 v[44:45], v[46:47], v[82:83]
	v_pk_mul_f32 v[46:47], v[48:49], v[84:85]
	v_cvt_pk_bf16_f32 v44, v44, v45
	v_cvt_pk_bf16_f32 v45, v46, v47
	ds_read_b64_tr_b16 v[180:181], v117 offset:17408
	ds_read_b64_tr_b16 v[182:183], v117 offset:18496
	ds_read_b64_tr_b16 v[184:185], v117 offset:17472
	ds_read_b64_tr_b16 v[186:187], v117 offset:18560
	ds_read_b64_tr_b16 v[188:189], v117 offset:17504
	ds_read_b64_tr_b16 v[190:191], v117 offset:18592
	ds_read_b64_tr_b16 v[192:193], v117 offset:17536
	ds_read_b64_tr_b16 v[194:195], v117 offset:18624
	ds_read_b64_tr_b16 v[196:197], v117 offset:17568
	ds_read_b64_tr_b16 v[198:199], v117 offset:18656
	ds_read_b64_tr_b16 v[200:201], v117 offset:17600
	ds_read_b64_tr_b16 v[202:203], v117 offset:18688
	ds_read_b64_tr_b16 v[204:205], v117 offset:17440
	ds_read_b64_tr_b16 v[206:207], v117 offset:18528
	ds_read_b64_tr_b16 v[208:209], v117 offset:17632
	ds_read_b64_tr_b16 v[210:211], v117 offset:18720
	s_waitcnt lgkmcnt(14)
	v_mfma_f32_16x16x32_bf16 v[78:81], v[180:183], v[42:45], v[78:81]
	s_waitcnt lgkmcnt(12)
	v_mfma_f32_16x16x32_bf16 v[62:65], v[184:187], v[42:45], v[62:65]
	s_waitcnt lgkmcnt(10)
	v_mfma_f32_16x16x32_bf16 v[54:57], v[188:191], v[42:45], v[54:57]
	s_waitcnt lgkmcnt(8)
	v_mfma_f32_16x16x32_bf16 v[70:73], v[192:195], v[42:45], v[70:73]
	s_waitcnt lgkmcnt(6)
	v_mfma_f32_16x16x32_bf16 v[58:61], v[196:199], v[42:45], v[58:61]
	s_waitcnt lgkmcnt(4)
	v_mfma_f32_16x16x32_bf16 v[50:53], v[200:203], v[42:45], v[50:53]
	s_waitcnt lgkmcnt(2)
	v_mfma_f32_16x16x32_bf16 v[74:77], v[204:207], v[42:45], v[74:77]
	s_waitcnt lgkmcnt(0)
	v_mfma_f32_16x16x32_bf16 v[86:89], v[208:211], v[42:45], v[86:89]
	s_and_b64 vcc, exec, s[72:73]
	s_cbranch_vccnz .LBB0_498
.LBB0_522:
	v_cndmask_b32_e64 v43, 0, v39, s[58:59]
	v_cndmask_b32_e64 v42, v38, 0, s[56:57]
	v_cndmask_b32_e64 v44, v40, 0, s[62:63]
	v_cndmask_b32_e64 v45, v41, 0, s[60:61]
	v_cndmask_b32_e64 v46, v34, 0, s[66:67]
	v_cndmask_b32_e64 v47, v35, 0, s[64:65]
	v_cndmask_b32_e64 v48, v36, 0, s[70:71]
	v_cndmask_b32_e64 v49, v37, 0, s[68:69]
	ds_read_b128 v[34:37], v118 offset:37248
	ds_read_b128 v[38:41], v118 offset:37264
	s_waitcnt lgkmcnt(1)
	v_pk_mul_f32 v[34:35], v[34:35], v[42:43]
	v_pk_mul_f32 v[36:37], v[36:37], v[44:45]
	v_cvt_pk_bf16_f32 v34, v34, v35
	v_cvt_pk_bf16_f32 v35, v36, v37
	s_waitcnt lgkmcnt(0)
	v_pk_mul_f32 v[36:37], v[38:39], v[46:47]
	v_pk_mul_f32 v[38:39], v[40:41], v[48:49]
	v_cvt_pk_bf16_f32 v36, v36, v37
	v_cvt_pk_bf16_f32 v37, v38, v39
	ds_read_b64_tr_b16 v[180:181], v117 offset:26112
	ds_read_b64_tr_b16 v[182:183], v117 offset:27200
	ds_read_b64_tr_b16 v[184:185], v117 offset:26176
	ds_read_b64_tr_b16 v[186:187], v117 offset:27264
	ds_read_b64_tr_b16 v[188:189], v117 offset:26208
	ds_read_b64_tr_b16 v[190:191], v117 offset:27296
	ds_read_b64_tr_b16 v[192:193], v117 offset:26240
	ds_read_b64_tr_b16 v[194:195], v117 offset:27328
	ds_read_b64_tr_b16 v[196:197], v117 offset:26272
	ds_read_b64_tr_b16 v[198:199], v117 offset:27360
	ds_read_b64_tr_b16 v[200:201], v117 offset:26304
	ds_read_b64_tr_b16 v[202:203], v117 offset:27392
	ds_read_b64_tr_b16 v[204:205], v117 offset:26144
	ds_read_b64_tr_b16 v[206:207], v117 offset:27232
	ds_read_b64_tr_b16 v[208:209], v117 offset:26336
	ds_read_b64_tr_b16 v[210:211], v117 offset:27424
	s_waitcnt lgkmcnt(14)
	v_mfma_f32_16x16x32_bf16 v[78:81], v[180:183], v[34:37], v[78:81]
	s_waitcnt lgkmcnt(12)
	v_mfma_f32_16x16x32_bf16 v[62:65], v[184:187], v[34:37], v[62:65]
	s_waitcnt lgkmcnt(10)
	v_mfma_f32_16x16x32_bf16 v[54:57], v[188:191], v[34:37], v[54:57]
	s_waitcnt lgkmcnt(8)
	v_mfma_f32_16x16x32_bf16 v[70:73], v[192:195], v[34:37], v[70:73]
	s_waitcnt lgkmcnt(6)
	v_mfma_f32_16x16x32_bf16 v[58:61], v[196:199], v[34:37], v[58:61]
	s_waitcnt lgkmcnt(4)
	v_mfma_f32_16x16x32_bf16 v[50:53], v[200:203], v[34:37], v[50:53]
	s_waitcnt lgkmcnt(2)
	v_mfma_f32_16x16x32_bf16 v[74:77], v[204:207], v[34:37], v[74:77]
	s_waitcnt lgkmcnt(0)
	v_mfma_f32_16x16x32_bf16 v[86:89], v[208:211], v[34:37], v[86:89]
	s_branch .LBB0_498

	.amdhsa_kernel _Z6mk_fwd4Args
		.amdhsa_group_segment_fixed_size 0
		.amdhsa_private_segment_fixed_size 0
		.amdhsa_kernarg_size 432
		.amdhsa_user_sgpr_count 2
		.amdhsa_user_sgpr_dispatch_ptr 0
		.amdhsa_user_sgpr_queue_ptr 0
		.amdhsa_user_sgpr_kernarg_segment_ptr 1
		.amdhsa_user_sgpr_dispatch_id 0
		.amdhsa_user_sgpr_kernarg_preload_length 0
		.amdhsa_user_sgpr_kernarg_preload_offset 0
		.amdhsa_user_sgpr_private_segment_size 0
		.amdhsa_uses_dynamic_stack 0
		.amdhsa_enable_private_segment 0
		.amdhsa_system_sgpr_workgroup_id_x 1
		.amdhsa_system_sgpr_workgroup_id_y 0
		.amdhsa_system_sgpr_workgroup_id_z 0
		.amdhsa_system_sgpr_workgroup_info 0
		.amdhsa_system_vgpr_workitem_id 2
		.amdhsa_next_free_vgpr 256
		.amdhsa_next_free_sgpr 102
		.amdhsa_accum_offset 256
		.amdhsa_reserve_vcc 1
		.amdhsa_float_round_mode_32 0
		.amdhsa_float_round_mode_16_64 0
		.amdhsa_float_denorm_mode_32 3
		.amdhsa_float_denorm_mode_16_64 3
		.amdhsa_dx10_clamp 1
		.amdhsa_ieee_mode 1
		.amdhsa_fp16_overflow 0
		.amdhsa_tg_split 0
		.amdhsa_exception_fp_ieee_invalid_op 0
		.amdhsa_exception_fp_denorm_src 0
		.amdhsa_exception_fp_ieee_div_zero 0
		.amdhsa_exception_fp_ieee_overflow 0
		.amdhsa_exception_fp_ieee_underflow 0
		.amdhsa_exception_fp_ieee_inexact 0
		.amdhsa_exception_int_div_zero 0
	.end_amdhsa_kernel

amdhsa.kernels:
  - .agpr_count:     0
    .args:
      - .offset:         0
        .size:           176
        .value_kind:     by_value
      - .offset:         176
        .size:           4
        .value_kind:     hidden_block_count_x
      - .offset:         180
        .size:           4
        .value_kind:     hidden_block_count_y
      - .offset:         184
        .size:           4
        .value_kind:     hidden_block_count_z
      - .offset:         188
        .size:           2
        .value_kind:     hidden_group_size_x
      - .offset:         190
        .size:           2
        .value_kind:     hidden_group_size_y
      - .offset:         192
        .size:           2
        .value_kind:     hidden_group_size_z
      - .offset:         194
        .size:           2
        .value_kind:     hidden_remainder_x
      - .offset:         196
        .size:           2
        .value_kind:     hidden_remainder_y
      - .offset:         198
        .size:           2
        .value_kind:     hidden_remainder_z
      - .offset:         216
        .size:           8
        .value_kind:     hidden_global_offset_x
      - .offset:         224
        .size:           8
        .value_kind:     hidden_global_offset_y
      - .offset:         232
        .size:           8
        .value_kind:     hidden_global_offset_z
      - .offset:         240
        .size:           2
        .value_kind:     hidden_grid_dims
      - .offset:         264
        .size:           8
        .value_kind:     hidden_multigrid_sync_arg
      - .offset:         296
        .size:           4
        .value_kind:     hidden_dynamic_lds_size
    .group_segment_fixed_size: 0
    .kernarg_segment_align: 8
    .kernarg_segment_size: 432
    .language:       OpenCL C
    .language_version:
      - 2
      - 0
    .max_flat_workgroup_size: 512
    .name:           _Z6mk_fwd4Args
    .private_segment_fixed_size: 0
    .sgpr_count:     108
    .sgpr_spill_count: 36
    .symbol:         _Z6mk_fwd4Args.kd
    .uniform_work_group_size: 1
    .uses_dynamic_stack: false
    .vgpr_count:     256
    .vgpr_spill_count: 0
    .wavefront_size: 64
